# P2 unit order: XCD pairs exchange rounds 1 and 6 (blockIdx^1) so no workgroup gets three q/k-norm tiles (max 3 -> 2 expensive epilogues on the critical path)
# speedup vs baseline: 1.0064x; 1.0026x over previous
.LBB0_154:
	s_mov_b32 s2, s97
	s_add_i32 s97, s97, 1
	s_mul_i32 s13, s97, s84
	s_mul_hi_u32 s20, s97, s85
	s_add_i32 s20, s20, s13
	s_mul_i32 s13, s97, s85
	s_add_u32 s66, s13, s24
	s_addc_u32 s67, s20, s86
	s_cmp_eq_u32 s97, 1
	s_cselect_b32 s13, 1, 0
	s_cmp_eq_u32 s97, 6
	s_cselect_b32 s13, 1, s13
	s_xor_b32 s66, s66, s13
	v_mov_b64_e32 v[0:1], 0x9c0
	s_cmp_lt_u32 s2, 0x3fffffff
	v_cmp_lt_i64_e32 vcc, s[66:67], v[0:1]
	s_cselect_b64 s[34:35], -1, 0
	s_and_b64 s[72:73], vcc, s[34:35]
	s_xor_b64 s[60:61], s[72:73], -1
	s_and_b64 vcc, exec, s[60:61]
	s_cbranch_vccnz .LBB0_156
	s_ashr_i32 s2, s66, 31
	s_lshr_b32 s2, s2, 29
	s_add_i32 s2, s66, s2
	s_ashr_i32 s13, s2, 3
	s_and_b32 s2, s2, -8
	s_sub_i32 s2, s66, s2
	s_cmp_lt_i32 s2, 0
	s_cselect_b32 s20, s90, 0x138
	s_mul_i32 s2, s2, s20
	s_add_i32 s2, s2, s13
	s_mul_hi_i32 s13, s2, 0x4ec4ec4f
	s_lshr_b32 s20, s13, 31
	s_ashr_i32 s13, s13, 6
	s_add_i32 s13, s13, s20
	s_lshl_b32 s20, s13, 2
	s_sub_i32 s34, 48, s20
	s_min_i32 s34, s34, 4
	s_abs_i32 s35, s34
	v_cvt_f32_u32_e32 v0, s35
	s_sub_i32 s63, 0, s35
	s_mulk_i32 s13, 0xd0
	s_sub_i32 s2, s2, s13
	v_rcp_iflag_f32_e32 v0, v0
	s_abs_i32 s13, s2
	s_xor_b32 s62, s2, s34
	s_ashr_i32 s62, s62, 31
	v_mul_f32_e32 v0, 0x4f7ffffe, v0
	v_cvt_u32_f32_e32 v0, v0
	s_nop 0
	v_readfirstlane_b32 s64, v0
	s_mul_i32 s63, s63, s64
	s_mul_hi_u32 s63, s64, s63
	s_add_i32 s64, s64, s63
	s_mul_hi_u32 s63, s13, s64
	s_mul_i32 s64, s63, s35
	s_sub_i32 s13, s13, s64
	s_add_i32 s65, s63, 1
	s_sub_i32 s64, s13, s35
	s_cmp_ge_u32 s13, s35
	s_cselect_b32 s63, s65, s63
	s_cselect_b32 s13, s64, s13
	s_add_i32 s64, s63, 1
	s_cmp_ge_u32 s13, s35
	s_cselect_b32 s13, s64, s63
	s_xor_b32 s13, s13, s62
	s_sub_i32 s62, s13, s62
	s_mul_i32 s13, s62, s34
	s_sub_i32 s2, s2, s13
	s_add_i32 s64, s20, s2
